# phase 2: cost-balanced unit-to-workgroup mapping (32 light workgroups take 12 cheap v/silu tiles, 224 heavy take 11) replacing round-robin with a 12th tail round
# speedup vs baseline: 1.0336x; 1.0052x over previous
.LBB0_215:
	s_and_b32 s2, s97, 7
	s_lshr_b32 s84, s97, 3
	s_cmp_eq_u32 s2, 0
	s_cbranch_scc1 .Lmap_li
	s_mov_b32 s85, 0
	s_mul_i32 s84, s84, 7
	s_add_u32 s84, s84, s2
	s_sub_u32 s84, s84, 1
	s_mov_b32 s83, 11
	s_branch .Lmap_id
.Lmap_li:
	s_mov_b32 s85, 1
	s_mov_b32 s83, 12
.Lmap_id:
	s_mov_b32 s82, 0
	s_add_u32 s22, s90, 0xec00000
	s_addc_u32 s23, s91, 0
	s_add_u32 s24, s90, 0x16c00000
	s_addc_u32 s25, s91, 0
	s_add_u32 s1, s90, 0x17e00000
	s_addc_u32 s54, s91, 0
	s_add_u32 s61, s90, 0x6c00000
	s_addc_u32 s62, s91, 0
	s_cmpk_gt_i32 s42, 0xb1f
	s_cbranch_scc1 .LBB0_377
	v_and_b32_e32 v1, 31, v0
	v_bfe_u32 v2, v0, 5, 1
	v_ashrrev_i32_e32 v3, 1, v0
	s_movk_i32 s2, 0xffc0
	v_and_or_b32 v169, v3, s2, v1
	v_lshlrev_b32_e32 v1, 3, v2
	v_lshlrev_b32_e32 v0, 2, v0
	s_movk_i32 s2, 0x100
	s_movk_i32 s43, 0x210
	s_add_u32 s8, s90, 0x2160000
	v_lshlrev_b32_e32 v168, 2, v2
	v_and_or_b32 v0, v0, s2, v1
	v_mul_lo_u32 v1, v169, s43
	s_addc_u32 s9, s91, 0
	v_mov_b32_e32 v171, 0
	v_or_b32_e32 v210, 1, v168
	v_or_b32_e32 v211, 2, v168
	v_or_b32_e32 v212, 3, v168
	v_or_b32_e32 v213, 8, v168
	v_or_b32_e32 v214, 9, v168
	v_or_b32_e32 v215, 10, v168
	v_or_b32_e32 v216, 11, v168
	v_or_b32_e32 v217, 16, v168
	v_or_b32_e32 v218, 17, v168
	v_or_b32_e32 v219, 18, v168
	v_or_b32_e32 v220, 19, v168
	v_or_b32_e32 v221, 24, v168
	v_or_b32_e32 v222, 25, v168
	v_or_b32_e32 v223, 26, v168
	v_or_b32_e32 v224, 27, v168
	v_or_b32_e32 v225, 32, v169
	s_movk_i32 s44, 0x90
	s_mov_b32 s45, 0xfffffc0
	s_movk_i32 s46, 0x80
	s_mov_b64 s[10:11], 0x20000
	s_mov_b32 s47, 0x20000
	s_mov_b32 s13, 0
	s_mov_b64 s[14:15], 0x40000
	s_mov_b32 s48, 0x40000
	s_mov_b64 s[16:17], 0x60000
	s_mov_b32 s49, 0x60000
	s_mov_b64 s[18:19], 0x100
	s_mov_b64 s[20:21], 0x20100
	s_mov_b64 s[28:29], 0x40100
	s_mov_b64 s[30:31], 0x60100
	s_mov_b32 s50, 0x12c00000
	v_mov_b32_e32 v226, 0x358637bd
	s_mov_b32 s51, 0x800000
	v_mbcnt_hi_u32_b32 v227, -1, v246
	v_add_u32_e32 v228, v0, v1
	s_branch .LBB0_220

.LBB0_219:
	v_readlane_b32 s2, v255, 6
	v_readlane_b32 s3, v255, 7
	s_add_i32 s82, s82, 1
	s_cmp_lt_i32 s82, s83
	s_cbranch_scc0 .LBB0_376
.LBB0_220:
	s_cmp_eq_u32 s85, 0
	s_cbranch_scc1 .Lmap_h
	s_lshl_b32 s2, s82, 5
	s_add_u32 s2, s2, s84
	s_cmp_lt_u32 s2, 0x80
	s_cbranch_scc0 .Lmap_l1
	s_mov_b32 s34, s2
	s_mov_b32 s36, 5
	s_branch .Lmap_lat
.Lmap_l1:
	s_cmp_lt_u32 s2, 0x90
	s_cbranch_scc0 .Lmap_l2
	s_sub_u32 s34, s2, 0x80
	s_mov_b32 s36, 5
	s_branch .Lmap_ctx
.Lmap_l2:
	s_sub_u32 s2, s2, 0x90
	s_lshr_b32 s34, s2, 1
	s_and_b32 s36, s2, 1
	s_add_u32 s36, s36, 14
	s_branch .Lmap_lat
.Lmap_h:
	s_mul_i32 s2, s82, 0xe0
	s_add_u32 s2, s2, s84
	s_cmp_lt_u32 s2, 0x8e8
	s_cbranch_scc0 .Lmap_h1
	s_mul_hi_u32 s34, s2, 0xd79435f
	s_mul_i32 s3, s34, 19
	s_sub_u32 s36, s2, s3
	s_cmp_lt_u32 s36, 5
	s_cbranch_scc1 .Lmap_lat
	s_cmp_lt_u32 s36, 13
	s_cselect_b32 s3, 1, 3
	s_add_u32 s36, s36, s3
	s_branch .Lmap_lat
.Lmap_h1:
	s_cmp_lt_u32 s2, 0x990
	s_cbranch_scc0 .Lmap_h2
	s_sub_u32 s2, s2, 0x8e8
	s_mul_hi_u32 s34, s2, 0xc30c30d
	s_mul_i32 s3, s34, 21
	s_sub_u32 s36, s2, s3
	s_add_u32 s34, s34, 0x78
	s_cmp_lt_u32 s36, 5
	s_cbranch_scc1 .Lmap_lat
	s_add_u32 s36, s36, 1
	s_branch .Lmap_lat
.Lmap_h2:
	s_sub_u32 s34, s2, 0x990
	s_mov_b32 s36, 4
.Lmap_ctx:
	s_mov_b64 s[26:27], -1
	s_mov_b64 s[38:39], 0
	s_mov_b64 s[2:3], 0x6400000
	s_branch .LBB0_224
.Lmap_lat:
	s_mov_b64 s[26:27], 0
	s_mov_b64 s[38:39], -1
	s_mov_b64 s[2:3], 0x2400000
